# prompt attention: first four Q fragments prefetched ahead of the tile barriers; static s_setprio 1 on waves 4-7 for the main loop
# speedup vs baseline: 1.0189x; 1.0080x over previous
; template <int DK, int DV, int KT, bool SAMPLE>
; DI void attn_item(CP c, int l, int qb, int h, unsigned char* sm) {
;     ...
;     const int ntiles = SAMPLE ? 66 : 2 * qb + 2; const int nj = ntiles / 2;
;     const bool wave_on = SAMPLE ? (wq < 2) : true;
;     const int qc = 2 * qb + (wq >> 1);
;     f32x16 Oacc[NDT];
; #pragma unroll
;     for (int d = 0; d < NDT; ++d)
; #pragma unroll
;         for (int i = 0; i < 16; ++i) Oacc[d][i] = 0.f;
;     float m_run = -INFINITY, l_run = 0.f;
;     const float scale = 0.07216878364870322f * 1.4426950408889634f;
;     u32x4 kreg[6], vreg[4];
;     const int lkey = gt >> 2, ls0 = gt & 3, ldv = gt >> 1, lv0 = gt & 1;
;     const bf16_t* kn_base = KNg + (size_t)lkey * 512 + h * 128 + ls0 * 8; const bf16_t* kp_base = KPEg + (size_t)lkey * 64 + ls0 * 8;
;     const bf16_t* vt_base = VTg + (size_t)(h * 128 + ldv) * MP + lv0 * 8;
;     ...
;     if (!SAMPLE) ATT_ISSUE(g);
.LBB0_645:
	s_or_b64 exec, exec, s[12:13]
	v_bfe_u32 v8, v167, 2, 6
	v_lshlrev_b32_e32 v0, 10, v8
	v_ashrrev_i32_e32 v154, 8, v167
	v_lshl_add_u64 v[2:3], s[54:55], 0, v[0:1]
	v_lshlrev_b32_e32 v152, 7, v5
	v_lshlrev_b32_e32 v0, 8, v5
	v_lshlrev_b32_e32 v5, 4, v167
	v_lshl_add_u64 v[2:3], v[2:3], 0, v[0:1]
	v_and_b32_e32 v0, 48, v5
	v_ashrrev_i32_e32 v155, 31, v154
	v_lshl_add_u64 v[156:157], v[2:3], 0, v[0:1]
	v_lshlrev_b32_e32 v2, 7, v8
	v_mov_b32_e32 v3, v1
	v_lshlrev_b64 v[6:7], 16, v[154:155]
	v_bfe_u32 v9, v167, 1, 7
	v_lshl_add_u64 v[2:3], s[56:57], 0, v[2:3]
	v_lshl_add_u64 v[6:7], v[156:157], 0, v[6:7]
	v_or_b32_e32 v10, v9, v152
	global_load_dwordx4 v[112:115], v[6:7], off
	global_load_dwordx4 v[116:119], v[6:7], off offset:64
	global_load_dwordx4 v[120:123], v[6:7], off offset:128
	global_load_dwordx4 v[124:127], v[6:7], off offset:192
	v_lshl_add_u64 v[158:159], v[2:3], 0, v[0:1]
	v_lshlrev_b64 v[6:7], 13, v[154:155]
	v_lshlrev_b32_e32 v2, 15, v10
	v_mov_b32_e32 v3, v1
	v_lshl_add_u64 v[6:7], v[158:159], 0, v[6:7]
	v_lshl_add_u64 v[2:3], s[58:59], 0, v[2:3]
	global_load_dwordx4 v[128:131], v[6:7], off
	global_load_dwordx4 v[132:135], v[6:7], off offset:64
	v_and_b32_e32 v6, 16, v5
	v_mov_b32_e32 v7, v1
	v_lshl_add_u64 v[164:165], v[2:3], 0, v[6:7]
	v_lshlrev_b64 v[2:3], 7, v[154:155]
	v_lshl_add_u64 v[2:3], v[164:165], 0, v[2:3]
	global_load_dwordx4 v[136:139], v[2:3], off
	global_load_dwordx4 v[140:143], v[2:3], off offset:32
	global_load_dwordx4 v[144:147], v[2:3], off offset:64
	global_load_dwordx4 v[148:151], v[2:3], off offset:96
	s_mov_b32 s12, 0xac00
	v_bfe_u32 v173, v167, 6, 2
	v_bfe_u32 v155, v167, 5, 1
	v_mad_i32_i24 v2, v154, s12, 0
	v_lshrrev_b32_e32 v172, 6, v167
	v_add_u32_e32 v3, 0xc800, v2
	v_add_u32_e32 v16, v2, v0
	v_lshlrev_b32_e32 v20, 4, v155
	v_lshl_or_b32 v0, v173, 5, v166
	v_bfe_u32 v5, v172, 1, 1
	v_add_u32_e32 v17, v3, v6
	v_mul_u32_u24_e32 v18, 0x190, v8
	v_mul_u32_u24_e32 v19, 0x90, v9
	v_add_u32_e32 v21, v2, v20
	v_mad_u32_u24 v22, v0, s14, 0
	v_lshl_add_u32 v23, v155, 3, v3
	v_mul_u32_u24_e32 v24, 0x190, v166
	v_mul_u32_u24_e32 v25, 0x90, v166
	v_mov_b32_e32 v14, v1
	v_mov_b32_e32 v15, v1
	v_lshl_or_b32 v175, v171, 1, v5
	v_sub_u32_e32 v176, 0x80, v4
	v_mov_b32_e32 v0, v1
	v_mov_b32_e32 v2, v1
	v_mov_b32_e32 v3, v1
	v_mov_b32_e32 v4, v1
	v_mov_b32_e32 v5, v1
	v_mov_b32_e32 v6, v1
	v_mov_b32_e32 v8, v1
	v_mov_b32_e32 v9, v1
	v_mov_b32_e32 v10, v1
	v_mov_b32_e32 v11, v1
	v_mov_b32_e32 v12, v1
	v_mov_b32_e32 v13, v1
	v_add_u32_e32 v178, v16, v18
	v_add_u32_e32 v179, v17, v19
	v_add_u32_e32 v180, v21, v24
	v_add_u32_e32 v181, v22, v20
	v_add_u32_e32 v182, v23, v25
	v_mov_b64_e32 v[30:31], v[14:15]
	v_mov_b64_e32 v[46:47], v[14:15]
	v_mov_b64_e32 v[62:63], v[14:15]
	v_mov_b64_e32 v[78:79], v[14:15]
	v_and_b32_e32 v174, 63, v167
	s_mov_b32 s14, 0
	v_mov_b32_e32 v183, 0xff800000
	v_mov_b32_e32 v177, 0
	s_mov_b64 s[12:13], 0
	v_mov_b32_e32 v246, v154
	v_mov_b64_e32 v[28:29], v[12:13]
	v_mov_b64_e32 v[26:27], v[10:11]
	v_mov_b64_e32 v[24:25], v[8:9]
	v_mov_b64_e32 v[22:23], v[6:7]
	v_mov_b64_e32 v[20:21], v[4:5]
	v_mov_b64_e32 v[18:19], v[2:3]
	v_mov_b64_e32 v[16:17], v[0:1]
	v_mov_b64_e32 v[44:45], v[12:13]
	v_mov_b64_e32 v[42:43], v[10:11]
	v_mov_b64_e32 v[40:41], v[8:9]
	v_mov_b64_e32 v[38:39], v[6:7]
	v_mov_b64_e32 v[36:37], v[4:5]
	v_mov_b64_e32 v[34:35], v[2:3]
	v_mov_b64_e32 v[32:33], v[0:1]
	v_mov_b64_e32 v[60:61], v[12:13]
	v_mov_b64_e32 v[58:59], v[10:11]
	v_mov_b64_e32 v[56:57], v[8:9]
	v_mov_b64_e32 v[54:55], v[6:7]
	v_mov_b64_e32 v[52:53], v[4:5]
	v_mov_b64_e32 v[50:51], v[2:3]
	v_mov_b64_e32 v[48:49], v[0:1]
	v_mov_b64_e32 v[76:77], v[12:13]
	v_mov_b64_e32 v[74:75], v[10:11]
	v_mov_b64_e32 v[72:73], v[8:9]
	v_mov_b64_e32 v[70:71], v[6:7]
	v_mov_b64_e32 v[68:69], v[4:5]
	v_mov_b64_e32 v[66:67], v[2:3]
	v_mov_b64_e32 v[64:65], v[0:1]
	v_readfirstlane_b32 s32, v154
	s_mov_b32 s41, 0
	s_lshl_b32 s40, s32, 16
	v_lshl_add_u64 v[156:157], v[156:157], 0, s[40:41]
	s_lshl_b32 s40, s32, 13
	v_lshl_add_u64 v[158:159], v[158:159], 0, s[40:41]
	s_lshl_b32 s40, s32, 7
	v_lshl_add_u64 v[164:165], v[164:165], 0, s[40:41]
	s_mov_b32 s40, 0x20000
	s_mov_b32 s42, 0x4000
	s_mov_b32 s43, 0
	s_movk_i32 s88, 0x100
	s_mov_b32 s89, 0
	ds_read_b128 v[80:83], v181
	ds_read_b128 v[214:217], v181 offset:32
	ds_read_b128 v[234:237], v181 offset:64
	ds_read_b128 v[238:241], v181 offset:96
	s_cmp_lg_u32 s32, 0
	s_cbranch_scc0 .Lprio_skip
	s_setprio 1

; template <int DK, int DV, int KT, bool SAMPLE>
; DI void attn_item(CP c, int l, int qb, int h, unsigned char* sm) {
;     ...
;     for (int j = 0; j < nj; ++j) {
;         const int kt = 2 * j + g;
;         lds_barrier();
;         if (!SAMPLE) {
; #pragma unroll
;             for (int i = 0; i < 6; ++i) *(u32x4*)(Ks + lkey * QS + ls0 * 8 + i * 32) = kreg[i];
; #pragma unroll
;             for (int i = 0; i < 4; ++i) *(u32x4*)(Vs + ldv * VS + lv0 * 8 + i * 16) = vreg[i];
;         } else {
;             const int k0 = kt * 32;
;             for (int v = gt; v < 32 * 40; v += 256) { const int key = v / 40, s = v % 40, kk = k0 + key; u32x4 o = (u32x4){0u, 0u, 0u, 0u};
;                 if (kk < 2048) { const float* src = s < 32 ? c->in[I_CLAT] + ((size_t)(l * 32 + b) * 2048 + kk) * 256 + s * 8 : c->in[I_CKPE] + ((size_t)(l * 32 + b) * 2048 + kk) * 64 + (s - 32) * 8;
;                     const f32x4 a = *(const f32x4*)src, bq = *(const f32x4*)(src + 4); o.x = pk2(a[0], a[1]); o.y = pk2(a[2], a[3]); o.z = pk2(bq[0], bq[1]); o.w = pk2(bq[2], bq[3]); }
;                 else if (kk < 2064) { const int rr = MP + b * 16 + (kk - 2048); o = *(const u32x4*)(s < 32 ? LATg + (size_t)rr * 256 + s * 8 : KPEg + (size_t)rr * 64 + (s - 32) * 8); }
;                 *(u32x4*)(Ks + key * QS + s * 8) = o; }
;             for (int v = gt; v < 256 * 4; v += 256) { const int dv = v >> 2, s = v & 3; u32x4 o = (u32x4){0u, 0u, 0u, 0u};
;                 if (k0 < LTS) o = *(const u32x4*)(LTg + ((size_t)b * 256 + dv) * LTS + k0 + s * 8);
;                 *(u32x4*)(Vs + dv * VS + s * 8) = o; }
;         }
;         lds_barrier();
;         if (!SAMPLE) { if (j + 1 < nj) ATT_ISSUE(kt + 2); }
;         const bool active = SAMPLE ? (wave_on && kt * 32 < 2064) : (kt <= qc);
;         if (active) {
;             f32x16 S[NMT];
; #pragma unroll
;             for (int mt = 0; mt < NMT; ++mt)
; #pragma unroll
;                 for (int i = 0; i < 16; ++i) S[mt][i] = 0.f;
;             {
;                 constexpr int NKP = DK / 32;
;                 bf16x8 Kf[2][2 * NMT]; bf16x8 Ql[2][2];
; #pragma unroll
;                 for (int e = 0; e < 2; ++e) {
; #pragma unroll
;                     for (int mt = 0; mt < NMT; ++mt) Kf[0][e * NMT + mt] = *(const bf16x8*)(Ks + (32 * mt + l31) * QS + 16 * e + 8 * hh);
.LBB0_646:
	s_or_b64 exec, exec, s[16:17]
	s_add_i32 s14, s14, 1
	v_cmp_eq_u32_e32 vcc, s14, v176
	s_or_b64 s[12:13], vcc, s[12:13]
	v_mov_b32_e32 v246, v2
	s_andn2_b64 exec, exec, s[12:13]
	s_cbranch_execz .LBB0_651
.LBB0_647:
	s_waitcnt lgkmcnt(0)
	s_barrier
	s_waitcnt vmcnt(9)
	ds_write_b128 v178, v[112:115] offset:51200
	s_waitcnt vmcnt(8)
	ds_write_b128 v178, v[116:119] offset:51264
	s_waitcnt vmcnt(7)
	ds_write_b128 v178, v[120:123] offset:51328
	s_waitcnt vmcnt(6)
	ds_write_b128 v178, v[124:127] offset:51392
	s_waitcnt vmcnt(5)
	ds_write_b128 v178, v[128:131] offset:51456
	s_waitcnt vmcnt(4)
	ds_write_b128 v178, v[132:135] offset:51520
	s_waitcnt vmcnt(3)
	ds_write_b128 v179, v[136:139] offset:25600
	s_waitcnt vmcnt(2)
	ds_write_b128 v179, v[140:143] offset:25632
	s_waitcnt vmcnt(1)
	ds_write_b128 v179, v[144:147] offset:25664
	s_waitcnt vmcnt(0)
	ds_write_b128 v179, v[148:151] offset:25696
	s_waitcnt lgkmcnt(0)
	s_barrier
	v_cmp_lt_u32_e32 vcc, s14, v171
	v_add_u32_e32 v2, 2, v246
	s_and_saveexec_b64 s[16:17], vcc
	s_cbranch_execz .LBB0_649
	v_lshl_add_u64 v[156:157], v[156:157], 0, s[40:41]
	v_lshl_add_u64 v[158:159], v[158:159], 0, s[42:43]
	v_lshl_add_u64 v[164:165], v[164:165], 0, s[88:89]
	ds_read_b128 v[4:7], v180 offset:51200
	ds_read_b128 v[8:11], v180 offset:51232
	ds_read_b128 v[12:15], v180 offset:64000
	ds_read_b128 v[184:187], v180 offset:64032
	ds_read_b128 v[218:221], v180 offset:51264
	ds_read_b128 v[222:225], v180 offset:51296
	ds_read_b128 v[226:229], v180 offset:64064
	ds_read_b128 v[230:233], v180 offset:64096
	s_waitcnt lgkmcnt(5)
	v_mfma_f32_32x32x16_bf16 v[96:111], v[4:7], v[80:83], 0
	v_mfma_f32_32x32x16_bf16 v[80:95], v[12:15], v[80:83], 0
	global_load_dwordx4 v[112:115], v[156:157], off
	s_waitcnt lgkmcnt(4)
	v_mfma_f32_32x32x16_bf16 v[96:111], v[8:11], v[214:217], v[96:111]
	v_mfma_f32_32x32x16_bf16 v[80:95], v[184:187], v[214:217], v[80:95]
	ds_read_b128 v[4:7], v180 offset:51328
	ds_read_b128 v[8:11], v180 offset:51360
	ds_read_b128 v[12:15], v180 offset:64128
	ds_read_b128 v[184:187], v180 offset:64160
	ds_read_b128 v[214:217], v181 offset:128
	ds_read_b128 v[242:245], v181 offset:160
	s_waitcnt lgkmcnt(7)
	v_mfma_f32_32x32x16_bf16 v[96:111], v[218:221], v[234:237], v[96:111]
	v_mfma_f32_32x32x16_bf16 v[80:95], v[226:229], v[234:237], v[80:95]
	global_load_dwordx4 v[116:119], v[156:157], off offset:64
	s_waitcnt lgkmcnt(6)
	v_mfma_f32_32x32x16_bf16 v[96:111], v[222:225], v[238:241], v[96:111]
	v_mfma_f32_32x32x16_bf16 v[80:95], v[230:233], v[238:241], v[80:95]
	ds_read_b128 v[218:221], v180 offset:51392
	ds_read_b128 v[222:225], v180 offset:51424
	ds_read_b128 v[226:229], v180 offset:64192
	ds_read_b128 v[230:233], v180 offset:64224
	ds_read_b128 v[234:237], v181 offset:192
	ds_read_b128 v[238:241], v181 offset:224
	s_waitcnt lgkmcnt(7)
	v_mfma_f32_32x32x16_bf16 v[96:111], v[4:7], v[214:217], v[96:111]
	v_mfma_f32_32x32x16_bf16 v[80:95], v[12:15], v[214:217], v[80:95]
	global_load_dwordx4 v[120:123], v[156:157], off offset:128
	s_waitcnt lgkmcnt(6)
	v_mfma_f32_32x32x16_bf16 v[96:111], v[8:11], v[242:245], v[96:111]
	v_mfma_f32_32x32x16_bf16 v[80:95], v[184:187], v[242:245], v[80:95]
	ds_read_b128 v[4:7], v180 offset:51456
	ds_read_b128 v[8:11], v180 offset:51488
	ds_read_b128 v[12:15], v180 offset:64256
	ds_read_b128 v[184:187], v180 offset:64288
	ds_read_b128 v[214:217], v181 offset:256
	ds_read_b128 v[242:245], v181 offset:288
	s_waitcnt lgkmcnt(7)
	v_mfma_f32_32x32x16_bf16 v[96:111], v[218:221], v[234:237], v[96:111]
	v_mfma_f32_32x32x16_bf16 v[80:95], v[226:229], v[234:237], v[80:95]
	global_load_dwordx4 v[124:127], v[156:157], off offset:192
	s_waitcnt lgkmcnt(6)
	v_mfma_f32_32x32x16_bf16 v[96:111], v[222:225], v[238:241], v[96:111]
	v_mfma_f32_32x32x16_bf16 v[80:95], v[230:233], v[238:241], v[80:95]
	ds_read_b128 v[218:221], v180 offset:51520
	ds_read_b128 v[222:225], v180 offset:51552
	ds_read_b128 v[226:229], v180 offset:64320
	ds_read_b128 v[230:233], v180 offset:64352
	ds_read_b128 v[234:237], v181 offset:320
	ds_read_b128 v[238:241], v181 offset:352
	s_waitcnt lgkmcnt(7)
	v_mfma_f32_32x32x16_bf16 v[96:111], v[4:7], v[214:217], v[96:111]
	v_mfma_f32_32x32x16_bf16 v[80:95], v[12:15], v[214:217], v[80:95]
	global_load_dwordx4 v[128:131], v[158:159], off
	s_waitcnt lgkmcnt(6)
	v_mfma_f32_32x32x16_bf16 v[96:111], v[8:11], v[242:245], v[96:111]
	v_mfma_f32_32x32x16_bf16 v[80:95], v[184:187], v[242:245], v[80:95]
	s_waitcnt lgkmcnt(1)
	v_mfma_f32_32x32x16_bf16 v[96:111], v[218:221], v[234:237], v[96:111]
	v_mfma_f32_32x32x16_bf16 v[80:95], v[226:229], v[234:237], v[80:95]
	global_load_dwordx4 v[132:135], v[158:159], off offset:64
	s_waitcnt lgkmcnt(0)
; DI unsigned pk2(float lo, float hi) { const hwf2_t v = {lo, hi}; const hwbf2_t b = __builtin_convertvector(v, hwbf2_t); return __builtin_bit_cast(unsigned, b); }
; #define ATT_LDV(buf, gi) do { const int _kg = (gi) / NDB, _db = (gi) % NDB; _Pragma("unroll") for (int d = 0; d < 4; ++d) { const bf16_t* vp = Vs + (32 * (4 * _db + d) + l31) * VS + 16 * _kg + 4 * hh; \
;                         const u32x2 lo = *(const u32x2*)vp, hi = *(const u32x2*)(vp + 8); Vf[buf][d].x = lo.x; Vf[buf][d].y = lo.y; Vf[buf][d].z = hi.x; Vf[buf][d].w = hi.y; } } while (0)
; template <int DK, int DV, int KT, bool SAMPLE>
; DI void attn_item(CP c, int l, int qb, int h, unsigned char* sm) {
;     ...
;             float mloc = -INFINITY;
; #pragma unroll
;             for (int mt = 0; mt < NMT; ++mt)
; #pragma unroll
;                 for (int i = 0; i < 16; ++i) { float s = S[mt][i] * scale;
;                     if (SAMPLE) { const int key = kt * KT + 32 * mt + (i & 3) + 8 * (i >> 2) + 4 * hh; if (key >= 2064) s = -INFINITY; }
;                     S[mt][i] = s; mloc = fmaxf(mloc, s); }
;             mloc = fmaxf(mloc, __shfl_xor(mloc, 32));
;             const float mnew = fmaxf(m_run, mloc); const float alpha = __builtin_amdgcn_exp2f(m_run - mnew); float psum = 0.f;
; #pragma unroll
;             for (int mt = 0; mt < NMT; ++mt)
; #pragma unroll
;                 for (int i = 0; i < 16; ++i) { const float p = __builtin_amdgcn_exp2f(S[mt][i] - mnew); S[mt][i] = p; psum += p; }
;             l_run = l_run * alpha + psum; m_run = mnew;
; #pragma unroll
;             for (int d = 0; d < NDT; ++d) Oacc[d] = Oacc[d] * alpha;
;             {
;                 constexpr int NDB = NDT / 4;
;                 constexpr int NG = 2 * NMT * NDB;
;                 u32x4 Vf[2][4];
;     ...
;                 ATT_LDV(0, 0);
; #pragma unroll
;                 for (int gi = 0; gi < NG; ++gi) { const int kg = gi / NDB, db = gi % NDB, mt = kg >> 1, s2 = kg & 1;
;                     if (gi + 1 < NG) ATT_LDV((gi + 1) & 1, gi + 1);
;                     u32x4 pw; pw.x = pk2(S[mt][8 * s2 + 0], S[mt][8 * s2 + 1]); pw.y = pk2(S[mt][8 * s2 + 2], S[mt][8 * s2 + 3]);
;                     pw.z = pk2(S[mt][8 * s2 + 4], S[mt][8 * s2 + 5]); pw.w = pk2(S[mt][8 * s2 + 6], S[mt][8 * s2 + 7]);
	v_mfma_f32_32x32x16_bf16 v[96:111], v[222:225], v[238:241], v[96:111]
	v_mfma_f32_32x32x16_bf16 v[80:95], v[230:233], v[238:241], v[80:95]
	s_nop 10
	s_mov_b32 s18, 0xff800000
	v_max3_f32 v0, v96, s18, v97
	v_max3_f32 v0, v0, v98, v99
	v_max3_f32 v0, v0, v100, v101
	v_max3_f32 v0, v0, v102, v103
	v_max3_f32 v0, v0, v104, v105
	v_max3_f32 v0, v0, v106, v107
	v_max3_f32 v0, v0, v108, v109
	v_max3_f32 v0, v0, v110, v111
	v_max3_f32 v0, v0, v80, v81
	v_max3_f32 v0, v0, v82, v83
	v_max3_f32 v0, v0, v84, v85
	v_max3_f32 v0, v0, v86, v87
	v_max3_f32 v0, v0, v88, v89
	v_max3_f32 v0, v0, v90, v91
	v_max3_f32 v0, v0, v92, v93
	v_max3_f32 v0, v0, v94, v95
	s_mov_b32 s18, 0x3dd53b94
	v_mul_f32_e32 v0, 0x3dd53b94, v0
	v_add_u32_e32 v226, 0x6000, v182
	v_mov_b32_e32 v3, v0
	v_mov_b32_e32 v4, v0
	v_add_u32_e32 v227, 0x7000, v182
	v_add_u32_e32 v228, 0x8800, v182
	v_permlane32_swap_b32_e32 v3, v4
	v_add_u32_e32 v229, 0x9800, v182
	v_max3_f32 v3, v183, v3, v4
	v_fma_f32 v4, v96, s18, -v3
	v_sub_f32_e32 v0, v183, v3
	v_exp_f32_e32 v183, v4
	v_fma_f32 v4, v97, s18, -v3
	v_exp_f32_e32 v184, v4
	v_fma_f32 v4, v98, s18, -v3
	v_exp_f32_e32 v185, v4
	v_fma_f32 v4, v99, s18, -v3
	v_exp_f32_e32 v186, v4
	v_fma_f32 v5, v100, s18, -v3
	v_add_f32_e32 v4, 0, v183
	v_exp_f32_e32 v187, v5
	v_fma_f32 v5, v101, s18, -v3
	v_add_f32_e32 v4, v184, v4
	v_exp_f32_e32 v192, v5
	v_fma_f32 v5, v102, s18, -v3
	v_add_f32_e32 v4, v185, v4
	v_exp_f32_e32 v193, v5
	v_fma_f32 v5, v103, s18, -v3
	v_add_f32_e32 v4, v186, v4
	v_exp_f32_e32 v103, v5
	v_fma_f32 v5, v104, s18, -v3
	v_add_f32_e32 v4, v187, v4
	v_exp_f32_e32 v104, v5
	v_fma_f32 v5, v105, s18, -v3
	v_add_f32_e32 v4, v192, v4
	v_exp_f32_e32 v105, v5
	v_fma_f32 v5, v106, s18, -v3
	v_add_f32_e32 v4, v193, v4
	v_exp_f32_e32 v106, v5
	v_fma_f32 v5, v107, s18, -v3
	v_add_f32_e32 v4, v103, v4
	v_exp_f32_e32 v107, v5
	v_fma_f32 v5, v108, s18, -v3
	v_add_f32_e32 v4, v104, v4
	v_exp_f32_e32 v108, v5
	v_fma_f32 v5, v109, s18, -v3
	v_add_f32_e32 v4, v105, v4
	v_exp_f32_e32 v109, v5
	v_fma_f32 v5, v110, s18, -v3
	v_add_f32_e32 v4, v106, v4
	v_exp_f32_e32 v110, v5
	v_fma_f32 v5, v111, s18, -v3
	v_add_f32_e32 v4, v107, v4
	v_exp_f32_e32 v111, v5
	v_fma_f32 v5, v80, s18, -v3
	v_add_f32_e32 v4, v108, v4
	v_exp_f32_e32 v204, v5
	v_fma_f32 v5, v81, s18, -v3
	v_add_f32_e32 v4, v109, v4
	v_exp_f32_e32 v205, v5
	v_fma_f32 v5, v82, s18, -v3
	v_add_f32_e32 v4, v110, v4
	v_exp_f32_e32 v206, v5
	v_fma_f32 v5, v83, s18, -v3
	v_add_f32_e32 v4, v111, v4
	v_exp_f32_e32 v207, v5
	v_fma_f32 v5, v84, s18, -v3
	v_exp_f32_e32 v213, v5
	v_fma_f32 v5, v85, s18, -v3
	v_add_f32_e32 v4, v204, v4
	v_exp_f32_e32 v214, v5
	v_fma_f32 v5, v86, s18, -v3
	v_add_f32_e32 v4, v205, v4
	v_exp_f32_e32 v215, v5
	v_fma_f32 v5, v87, s18, -v3
	v_add_f32_e32 v4, v206, v4
	v_exp_f32_e32 v216, v5
	v_fma_f32 v5, v88, s18, -v3
	v_add_f32_e32 v4, v207, v4
	v_exp_f32_e32 v217, v5
	v_fma_f32 v5, v89, s18, -v3
	v_add_f32_e32 v4, v213, v4
	v_exp_f32_e32 v218, v5
	v_fma_f32 v5, v90, s18, -v3
	v_add_f32_e32 v4, v214, v4
	v_exp_f32_e32 v219, v5
	v_fma_f32 v5, v91, s18, -v3
	v_add_f32_e32 v4, v215, v4
	v_exp_f32_e32 v220, v5
	v_fma_f32 v5, v92, s18, -v3
	v_add_f32_e32 v4, v216, v4
	v_exp_f32_e32 v221, v5
	v_fma_f32 v5, v93, s18, -v3
	v_add_f32_e32 v4, v217, v4
	v_exp_f32_e32 v222, v5
	v_fma_f32 v5, v94, s18, -v3
	v_add_f32_e32 v4, v218, v4
	v_exp_f32_e32 v223, v5
	v_fma_f32 v5, v95, s18, -v3
	v_add_f32_e32 v4, v219, v4
	v_exp_f32_e32 v224, v5
	v_add_f32_e32 v4, v220, v4
	v_add_f32_e32 v4, v221, v4
	v_add_f32_e32 v4, v222, v4
	v_add_f32_e32 v4, v223, v4
	v_add_f32_e32 v225, v224, v4
	ds_read2_b64 v[4:7], v226 offset0:128 offset1:130
	ds_read2_b64 v[8:11], v226 offset0:132 offset1:134
	ds_read2_b64 v[12:15], v227 offset0:192 offset1:194
	ds_read2_b64 v[80:83], v228 offset1:2
	ds_read2_b64 v[84:87], v229 offset0:64 offset1:66
	ds_read2_b64 v[88:91], v227 offset0:196 offset1:198
	ds_read2_b64 v[92:95], v228 offset0:4 offset1:6
	ds_read2_b64 v[96:99], v229 offset0:68 offset1:70
	v_exp_f32_e32 v0, v0
	v_cvt_pk_bf16_f32 v100, v183, v184
	v_cvt_pk_bf16_f32 v101, v185, v186
	v_cvt_pk_bf16_f32 v102, v187, v192
	v_pk_mul_f32 v[78:79], v[78:79], v[0:1] op_sel_hi:[1,0]
	v_pk_mul_f32 v[76:77], v[76:77], v[0:1] op_sel_hi:[1,0]
	v_pk_mul_f32 v[74:75], v[74:75], v[0:1] op_sel_hi:[1,0]
	v_pk_mul_f32 v[72:73], v[72:73], v[0:1] op_sel_hi:[1,0]
	v_pk_mul_f32 v[70:71], v[70:71], v[0:1] op_sel_hi:[1,0]
	v_pk_mul_f32 v[68:69], v[68:69], v[0:1] op_sel_hi:[1,0]
	v_pk_mul_f32 v[66:67], v[66:67], v[0:1] op_sel_hi:[1,0]
	v_pk_mul_f32 v[64:65], v[64:65], v[0:1] op_sel_hi:[1,0]
	v_pk_mul_f32 v[62:63], v[62:63], v[0:1] op_sel_hi:[1,0]
	v_pk_mul_f32 v[60:61], v[60:61], v[0:1] op_sel_hi:[1,0]
	v_pk_mul_f32 v[58:59], v[58:59], v[0:1] op_sel_hi:[1,0]
	v_pk_mul_f32 v[56:57], v[56:57], v[0:1] op_sel_hi:[1,0]
	v_pk_mul_f32 v[54:55], v[54:55], v[0:1] op_sel_hi:[1,0]
	v_pk_mul_f32 v[52:53], v[52:53], v[0:1] op_sel_hi:[1,0]
	v_pk_mul_f32 v[50:51], v[50:51], v[0:1] op_sel_hi:[1,0]
	v_pk_mul_f32 v[48:49], v[48:49], v[0:1] op_sel_hi:[1,0]
	v_pk_mul_f32 v[46:47], v[46:47], v[0:1] op_sel_hi:[1,0]
	v_pk_mul_f32 v[44:45], v[44:45], v[0:1] op_sel_hi:[1,0]
	v_pk_mul_f32 v[42:43], v[42:43], v[0:1] op_sel_hi:[1,0]
	v_pk_mul_f32 v[40:41], v[40:41], v[0:1] op_sel_hi:[1,0]
	v_pk_mul_f32 v[38:39], v[38:39], v[0:1] op_sel_hi:[1,0]
	v_pk_mul_f32 v[36:37], v[36:37], v[0:1] op_sel_hi:[1,0]
	v_pk_mul_f32 v[34:35], v[34:35], v[0:1] op_sel_hi:[1,0]
	v_pk_mul_f32 v[32:33], v[32:33], v[0:1] op_sel_hi:[1,0]
	v_pk_mul_f32 v[30:31], v[30:31], v[0:1] op_sel_hi:[1,0]
	v_pk_mul_f32 v[28:29], v[28:29], v[0:1] op_sel_hi:[1,0]
	v_pk_mul_f32 v[26:27], v[26:27], v[0:1] op_sel_hi:[1,0]
	v_pk_mul_f32 v[24:25], v[24:25], v[0:1] op_sel_hi:[1,0]
	v_pk_mul_f32 v[22:23], v[22:23], v[0:1] op_sel_hi:[1,0]
	v_pk_mul_f32 v[20:21], v[20:21], v[0:1] op_sel_hi:[1,0]
	v_pk_mul_f32 v[18:19], v[18:19], v[0:1] op_sel_hi:[1,0]
	v_pk_mul_f32 v[16:17], v[16:17], v[0:1] op_sel_hi:[1,0]
	v_cvt_pk_bf16_f32 v103, v193, v103
	s_waitcnt lgkmcnt(7)
; template <int DK, int DV, int KT, bool SAMPLE>
; DI void attn_item(CP c, int l, int qb, int h, unsigned char* sm) {
;     ...
;             {
;                 constexpr int NKP = DK / 32;
;                 bf16x8 Kf[2][2 * NMT]; bf16x8 Ql[2][2];
; #pragma unroll
;                 for (int e = 0; e < 2; ++e) {
; #pragma unroll
;                     for (int mt = 0; mt < NMT; ++mt) Kf[0][e * NMT + mt] = *(const bf16x8*)(Ks + (32 * mt + l31) * QS + 16 * e + 8 * hh);
;                     if (!QREG) Ql[0][e] = *(const bf16x8*)(Qs + (32 * wq + l31) * QS + 16 * e + 8 * hh); }
; #pragma unroll
;                 for (int kp = 0; kp < NKP; ++kp) {
;                     if (kp + 1 < NKP) {
; #pragma unroll
;                         for (int e = 0; e < 2; ++e) {
; #pragma unroll
;                             for (int mt = 0; mt < NMT; ++mt) Kf[(kp + 1) & 1][e * NMT + mt] = *(const bf16x8*)(Ks + (32 * mt + l31) * QS + 16 * (2 * kp + 2 + e) + 8 * hh);
;                             if (!QREG) Ql[(kp + 1) & 1][e] = *(const bf16x8*)(Qs + (32 * wq + l31) * QS + 16 * (2 * kp + 2 + e) + 8 * hh); } }
;                     __builtin_amdgcn_sched_barrier(0);
; #pragma unroll
;                     for (int e = 0; e < 2; ++e)
; #pragma unroll
;                         for (int mt = 0; mt < NMT; ++mt) S[mt] = __builtin_amdgcn_mfma_f32_32x32x16_bf16(Kf[kp & 1][e * NMT + mt], !QREG ? Ql[kp & 1][e] : Qf[QREG ? 2 * kp + e : 0], S[mt], 0, 0, 0);
;                     __builtin_amdgcn_sched_barrier(0);
;     ...
;                 for (int gi = 0; gi < NG; ++gi) { const int kg = gi / NDB, db = gi % NDB, mt = kg >> 1, s2 = kg & 1;
;                     if (gi + 1 < NG) ATT_LDV((gi + 1) & 1, gi + 1);
;                     u32x4 pw; pw.x = pk2(S[mt][8 * s2 + 0], S[mt][8 * s2 + 1]); pw.y = pk2(S[mt][8 * s2 + 2], S[mt][8 * s2 + 3]);
;                     pw.z = pk2(S[mt][8 * s2 + 4], S[mt][8 * s2 + 5]); pw.w = pk2(S[mt][8 * s2 + 6], S[mt][8 * s2 + 7]);
;                     const bf16x8 pf = __builtin_bit_cast(bf16x8, pw);
;                     __builtin_amdgcn_sched_barrier(0);
; #pragma unroll
;                     for (int d = 0; d < 4; ++d) Oacc[4 * db + d] = __builtin_amdgcn_mfma_f32_32x32x16_bf16(__builtin_bit_cast(bf16x8, Vf[gi & 1][d]), pf, Oacc[4 * db + d], 0, 0, 0);
;                     __builtin_amdgcn_sched_barrier(0);
;                 }
	s_nop 0
	v_mfma_f32_32x32x16_bf16 v[64:79], v[4:7], v[100:103], v[64:79]
	s_waitcnt lgkmcnt(5)
	v_mfma_f32_32x32x16_bf16 v[48:63], v[12:15], v[100:103], v[48:63]
	global_load_dwordx4 v[136:139], v[164:165], off
	s_waitcnt lgkmcnt(4)
	v_mfma_f32_32x32x16_bf16 v[32:47], v[80:83], v[100:103], v[32:47]
	s_waitcnt lgkmcnt(3)
	v_mfma_f32_32x32x16_bf16 v[16:31], v[84:87], v[100:103], v[16:31]
	ds_read2_b64 v[4:7], v226 offset0:136 offset1:138
	ds_read2_b64 v[12:15], v227 offset0:200 offset1:202
	ds_read2_b64 v[80:83], v228 offset0:8 offset1:10
	ds_read2_b64 v[84:87], v229 offset0:72 offset1:74
	v_cvt_pk_bf16_f32 v100, v104, v105
	v_cvt_pk_bf16_f32 v101, v106, v107
	v_cvt_pk_bf16_f32 v102, v108, v109
	v_cvt_pk_bf16_f32 v103, v110, v111
	s_nop 1
	v_mfma_f32_32x32x16_bf16 v[64:79], v[8:11], v[100:103], v[64:79]
	s_waitcnt lgkmcnt(6)
	v_mfma_f32_32x32x16_bf16 v[48:63], v[88:91], v[100:103], v[48:63]
	global_load_dwordx4 v[140:143], v[164:165], off offset:32
	s_waitcnt lgkmcnt(5)
	v_mfma_f32_32x32x16_bf16 v[32:47], v[92:95], v[100:103], v[32:47]
	s_waitcnt lgkmcnt(4)
	v_mfma_f32_32x32x16_bf16 v[16:31], v[96:99], v[100:103], v[16:31]
	ds_read2_b64 v[8:11], v226 offset0:140 offset1:142
	ds_read2_b64 v[88:91], v227 offset0:204 offset1:206
	ds_read2_b64 v[92:95], v228 offset0:12 offset1:14
	ds_read2_b64 v[96:99], v229 offset0:76 offset1:78
	v_cvt_pk_bf16_f32 v100, v204, v205
	v_cvt_pk_bf16_f32 v101, v206, v207
	v_cvt_pk_bf16_f32 v102, v213, v214
	v_cvt_pk_bf16_f32 v103, v215, v216
	s_waitcnt lgkmcnt(7)
	s_nop 0
	v_mfma_f32_32x32x16_bf16 v[64:79], v[4:7], v[100:103], v[64:79]
	s_waitcnt lgkmcnt(6)
	v_mfma_f32_32x32x16_bf16 v[48:63], v[12:15], v[100:103], v[48:63]
	global_load_dwordx4 v[144:147], v[164:165], off offset:64
	s_waitcnt lgkmcnt(5)
	v_mfma_f32_32x32x16_bf16 v[32:47], v[80:83], v[100:103], v[32:47]
	s_waitcnt lgkmcnt(4)
	v_mfma_f32_32x32x16_bf16 v[16:31], v[84:87], v[100:103], v[16:31]
	v_cvt_pk_bf16_f32 v4, v217, v218
	v_cvt_pk_bf16_f32 v5, v219, v220
	v_cvt_pk_bf16_f32 v6, v221, v222
	v_cvt_pk_bf16_f32 v7, v223, v224
	s_waitcnt lgkmcnt(3)
	s_nop 0
	v_mfma_f32_32x32x16_bf16 v[64:79], v[8:11], v[4:7], v[64:79]
	s_waitcnt lgkmcnt(2)
	v_mfma_f32_32x32x16_bf16 v[48:63], v[88:91], v[4:7], v[48:63]
	global_load_dwordx4 v[148:151], v[164:165], off offset:96
	s_waitcnt lgkmcnt(1)
	v_mfma_f32_32x32x16_bf16 v[32:47], v[92:95], v[4:7], v[32:47]
	s_waitcnt lgkmcnt(0)
	v_mfma_f32_32x32x16_bf16 v[16:31], v[96:99], v[4:7], v[16:31]
	ds_read_b128 v[80:83], v181
	ds_read_b128 v[214:217], v181 offset:32
	ds_read_b128 v[234:237], v181 offset:64
	ds_read_b128 v[238:241], v181 offset:96
	v_fmac_f32_e32 v225, v177, v0
	v_mov_b32_e32 v177, v225
	v_mov_b32_e32 v183, v3
	s_branch .LBB0_646
.LBB0_649:
	s_or_b64 exec, exec, s[16:17]
	v_cmp_le_i32_e32 vcc, v246, v175
	s_and_saveexec_b64 s[16:17], vcc
	s_cbranch_execz .LBB0_646
	ds_read_b128 v[4:7], v180 offset:51200
	ds_read_b128 v[8:11], v180 offset:51232
	ds_read_b128 v[12:15], v180 offset:64000
	ds_read_b128 v[184:187], v180 offset:64032
	ds_read_b128 v[218:221], v180 offset:51264
	ds_read_b128 v[222:225], v180 offset:51296
	ds_read_b128 v[226:229], v180 offset:64064
	ds_read_b128 v[230:233], v180 offset:64096
	s_waitcnt lgkmcnt(5)
	v_mfma_f32_32x32x16_bf16 v[96:111], v[4:7], v[80:83], 0
	v_mfma_f32_32x32x16_bf16 v[80:95], v[12:15], v[80:83], 0
	s_waitcnt lgkmcnt(4)
	v_mfma_f32_32x32x16_bf16 v[96:111], v[8:11], v[214:217], v[96:111]
	v_mfma_f32_32x32x16_bf16 v[80:95], v[184:187], v[214:217], v[80:95]
	ds_read_b128 v[4:7], v180 offset:51328
	ds_read_b128 v[8:11], v180 offset:51360
	ds_read_b128 v[12:15], v180 offset:64128
	ds_read_b128 v[184:187], v180 offset:64160
	ds_read_b128 v[214:217], v181 offset:128
	ds_read_b128 v[242:245], v181 offset:160
	s_waitcnt lgkmcnt(7)
	v_mfma_f32_32x32x16_bf16 v[96:111], v[218:221], v[234:237], v[96:111]
	v_mfma_f32_32x32x16_bf16 v[80:95], v[226:229], v[234:237], v[80:95]
	s_waitcnt lgkmcnt(6)
	v_mfma_f32_32x32x16_bf16 v[96:111], v[222:225], v[238:241], v[96:111]
	v_mfma_f32_32x32x16_bf16 v[80:95], v[230:233], v[238:241], v[80:95]
	ds_read_b128 v[218:221], v180 offset:51392
	ds_read_b128 v[222:225], v180 offset:51424
	ds_read_b128 v[226:229], v180 offset:64192
	ds_read_b128 v[230:233], v180 offset:64224
	ds_read_b128 v[234:237], v181 offset:192
	ds_read_b128 v[238:241], v181 offset:224
	s_waitcnt lgkmcnt(7)
	v_mfma_f32_32x32x16_bf16 v[96:111], v[4:7], v[214:217], v[96:111]
	v_mfma_f32_32x32x16_bf16 v[80:95], v[12:15], v[214:217], v[80:95]
	s_waitcnt lgkmcnt(6)
	v_mfma_f32_32x32x16_bf16 v[96:111], v[8:11], v[242:245], v[96:111]
	v_mfma_f32_32x32x16_bf16 v[80:95], v[184:187], v[242:245], v[80:95]
	ds_read_b128 v[4:7], v180 offset:51456
	ds_read_b128 v[8:11], v180 offset:51488
	ds_read_b128 v[12:15], v180 offset:64256
	ds_read_b128 v[184:187], v180 offset:64288
	ds_read_b128 v[214:217], v181 offset:256
	ds_read_b128 v[242:245], v181 offset:288
	s_waitcnt lgkmcnt(7)
	v_mfma_f32_32x32x16_bf16 v[96:111], v[218:221], v[234:237], v[96:111]
	v_mfma_f32_32x32x16_bf16 v[80:95], v[226:229], v[234:237], v[80:95]
	s_waitcnt lgkmcnt(6)
	v_mfma_f32_32x32x16_bf16 v[96:111], v[222:225], v[238:241], v[96:111]
	v_mfma_f32_32x32x16_bf16 v[80:95], v[230:233], v[238:241], v[80:95]
	ds_read_b128 v[218:221], v180 offset:51520
	ds_read_b128 v[222:225], v180 offset:51552
	ds_read_b128 v[226:229], v180 offset:64320
	ds_read_b128 v[230:233], v180 offset:64352
	ds_read_b128 v[234:237], v181 offset:320
	ds_read_b128 v[238:241], v181 offset:352
	s_waitcnt lgkmcnt(7)
	v_mfma_f32_32x32x16_bf16 v[96:111], v[4:7], v[214:217], v[96:111]
	v_mfma_f32_32x32x16_bf16 v[80:95], v[12:15], v[214:217], v[80:95]
	s_waitcnt lgkmcnt(6)
; DI unsigned pk2(float lo, float hi) { const hwf2_t v = {lo, hi}; const hwbf2_t b = __builtin_convertvector(v, hwbf2_t); return __builtin_bit_cast(unsigned, b); }
; #define ATT_LDV(buf, gi) do { const int _kg = (gi) / NDB, _db = (gi) % NDB; _Pragma("unroll") for (int d = 0; d < 4; ++d) { const bf16_t* vp = Vs + (32 * (4 * _db + d) + l31) * VS + 16 * _kg + 4 * hh; \
;                         const u32x2 lo = *(const u32x2*)vp, hi = *(const u32x2*)(vp + 8); Vf[buf][d].x = lo.x; Vf[buf][d].y = lo.y; Vf[buf][d].z = hi.x; Vf[buf][d].w = hi.y; } } while (0)
; template <int DK, int DV, int KT, bool SAMPLE>
; DI void attn_item(CP c, int l, int qb, int h, unsigned char* sm) {
;     ...
;             float mloc = -INFINITY;
; #pragma unroll
;             for (int mt = 0; mt < NMT; ++mt)
; #pragma unroll
;                 for (int i = 0; i < 16; ++i) { float s = S[mt][i] * scale;
;                     if (SAMPLE) { const int key = kt * KT + 32 * mt + (i & 3) + 8 * (i >> 2) + 4 * hh; if (key >= 2064) s = -INFINITY; }
;                     S[mt][i] = s; mloc = fmaxf(mloc, s); }
;             mloc = fmaxf(mloc, __shfl_xor(mloc, 32));
;             const float mnew = fmaxf(m_run, mloc); const float alpha = __builtin_amdgcn_exp2f(m_run - mnew); float psum = 0.f;
; #pragma unroll
;             for (int mt = 0; mt < NMT; ++mt)
; #pragma unroll
;                 for (int i = 0; i < 16; ++i) { const float p = __builtin_amdgcn_exp2f(S[mt][i] - mnew); S[mt][i] = p; psum += p; }
;             l_run = l_run * alpha + psum; m_run = mnew;
; #pragma unroll
;             for (int d = 0; d < NDT; ++d) Oacc[d] = Oacc[d] * alpha;
;             {
;                 constexpr int NDB = NDT / 4;
;                 constexpr int NG = 2 * NMT * NDB;
;                 u32x4 Vf[2][4];
;     ...
;                 ATT_LDV(0, 0);
; #pragma unroll
;                 for (int gi = 0; gi < NG; ++gi) { const int kg = gi / NDB, db = gi % NDB, mt = kg >> 1, s2 = kg & 1;
;                     if (gi + 1 < NG) ATT_LDV((gi + 1) & 1, gi + 1);
;                     u32x4 pw; pw.x = pk2(S[mt][8 * s2 + 0], S[mt][8 * s2 + 1]); pw.y = pk2(S[mt][8 * s2 + 2], S[mt][8 * s2 + 3]);
;                     pw.z = pk2(S[mt][8 * s2 + 4], S[mt][8 * s2 + 5]); pw.w = pk2(S[mt][8 * s2 + 6], S[mt][8 * s2 + 7]);
	v_mfma_f32_32x32x16_bf16 v[96:111], v[8:11], v[242:245], v[96:111]
	v_mfma_f32_32x32x16_bf16 v[80:95], v[184:187], v[242:245], v[80:95]
	s_waitcnt lgkmcnt(1)
	v_mfma_f32_32x32x16_bf16 v[96:111], v[218:221], v[234:237], v[96:111]
	v_mfma_f32_32x32x16_bf16 v[80:95], v[226:229], v[234:237], v[80:95]
	s_waitcnt lgkmcnt(0)
	v_mfma_f32_32x32x16_bf16 v[96:111], v[222:225], v[238:241], v[96:111]
	v_mfma_f32_32x32x16_bf16 v[80:95], v[230:233], v[238:241], v[80:95]
	s_nop 10
	s_mov_b32 s18, 0xff800000
	v_max3_f32 v0, v96, s18, v97
	v_max3_f32 v0, v0, v98, v99
	v_max3_f32 v0, v0, v100, v101
	v_max3_f32 v0, v0, v102, v103
	v_max3_f32 v0, v0, v104, v105
	v_max3_f32 v0, v0, v106, v107
	v_max3_f32 v0, v0, v108, v109
	v_max3_f32 v0, v0, v110, v111
	v_max3_f32 v0, v0, v80, v81
	v_max3_f32 v0, v0, v82, v83
	v_max3_f32 v0, v0, v84, v85
	v_max3_f32 v0, v0, v86, v87
	v_max3_f32 v0, v0, v88, v89
	v_max3_f32 v0, v0, v90, v91
	v_max3_f32 v0, v0, v92, v93
	v_max3_f32 v0, v0, v94, v95
	s_mov_b32 s18, 0x3dd53b94
	v_mul_f32_e32 v0, 0x3dd53b94, v0
	v_add_u32_e32 v226, 0x6000, v182
	v_mov_b32_e32 v3, v0
	v_mov_b32_e32 v4, v0
	v_add_u32_e32 v227, 0x7000, v182
	v_add_u32_e32 v228, 0x8800, v182
	v_permlane32_swap_b32_e32 v3, v4
	v_add_u32_e32 v229, 0x9800, v182
	v_max3_f32 v3, v183, v3, v4
	v_fma_f32 v4, v96, s18, -v3
	v_sub_f32_e32 v0, v183, v3
	v_exp_f32_e32 v183, v4
	v_fma_f32 v4, v97, s18, -v3
	v_exp_f32_e32 v184, v4
	v_fma_f32 v4, v98, s18, -v3
	v_exp_f32_e32 v185, v4
	v_fma_f32 v4, v99, s18, -v3
	v_exp_f32_e32 v186, v4
	v_fma_f32 v5, v100, s18, -v3
	v_add_f32_e32 v4, 0, v183
	v_exp_f32_e32 v187, v5
	v_fma_f32 v5, v101, s18, -v3
	v_add_f32_e32 v4, v184, v4
	v_exp_f32_e32 v192, v5
	v_fma_f32 v5, v102, s18, -v3
	v_add_f32_e32 v4, v185, v4
	v_exp_f32_e32 v193, v5
	v_fma_f32 v5, v103, s18, -v3
	v_add_f32_e32 v4, v186, v4
	v_exp_f32_e32 v103, v5
	v_fma_f32 v5, v104, s18, -v3
	v_add_f32_e32 v4, v187, v4
	v_exp_f32_e32 v104, v5
	v_fma_f32 v5, v105, s18, -v3
	v_add_f32_e32 v4, v192, v4
	v_exp_f32_e32 v105, v5
	v_fma_f32 v5, v106, s18, -v3
	v_add_f32_e32 v4, v193, v4
	v_exp_f32_e32 v106, v5
	v_fma_f32 v5, v107, s18, -v3
	v_add_f32_e32 v4, v103, v4
	v_exp_f32_e32 v107, v5
	v_fma_f32 v5, v108, s18, -v3
	v_add_f32_e32 v4, v104, v4
	v_exp_f32_e32 v108, v5
	v_fma_f32 v5, v109, s18, -v3
	v_add_f32_e32 v4, v105, v4
	v_exp_f32_e32 v109, v5
	v_fma_f32 v5, v110, s18, -v3
	v_add_f32_e32 v4, v106, v4
	v_exp_f32_e32 v110, v5
	v_fma_f32 v5, v111, s18, -v3
	v_add_f32_e32 v4, v107, v4
	v_exp_f32_e32 v111, v5
	v_fma_f32 v5, v80, s18, -v3
	v_add_f32_e32 v4, v108, v4
	v_exp_f32_e32 v204, v5
	v_fma_f32 v5, v81, s18, -v3
	v_add_f32_e32 v4, v109, v4
	v_exp_f32_e32 v205, v5
	v_fma_f32 v5, v82, s18, -v3
	v_add_f32_e32 v4, v110, v4
	v_exp_f32_e32 v206, v5
	v_fma_f32 v5, v83, s18, -v3
	v_add_f32_e32 v4, v111, v4
	v_exp_f32_e32 v207, v5
	v_fma_f32 v5, v84, s18, -v3
	v_exp_f32_e32 v213, v5
	v_fma_f32 v5, v85, s18, -v3
	v_add_f32_e32 v4, v204, v4
	v_exp_f32_e32 v214, v5
	v_fma_f32 v5, v86, s18, -v3
	v_add_f32_e32 v4, v205, v4
	v_exp_f32_e32 v215, v5
	v_fma_f32 v5, v87, s18, -v3
	v_add_f32_e32 v4, v206, v4
	v_exp_f32_e32 v216, v5
	v_fma_f32 v5, v88, s18, -v3
	v_add_f32_e32 v4, v207, v4
	v_exp_f32_e32 v217, v5
	v_fma_f32 v5, v89, s18, -v3
	v_add_f32_e32 v4, v213, v4
	v_exp_f32_e32 v218, v5
	v_fma_f32 v5, v90, s18, -v3
	v_add_f32_e32 v4, v214, v4
	v_exp_f32_e32 v219, v5
	v_fma_f32 v5, v91, s18, -v3
	v_add_f32_e32 v4, v215, v4
	v_exp_f32_e32 v220, v5
	v_fma_f32 v5, v92, s18, -v3
	v_add_f32_e32 v4, v216, v4
	v_exp_f32_e32 v221, v5
	v_fma_f32 v5, v93, s18, -v3
	v_add_f32_e32 v4, v217, v4
	v_exp_f32_e32 v222, v5
	v_fma_f32 v5, v94, s18, -v3
	v_add_f32_e32 v4, v218, v4
	v_exp_f32_e32 v223, v5
	v_fma_f32 v5, v95, s18, -v3
	v_add_f32_e32 v4, v219, v4
	v_exp_f32_e32 v224, v5
	v_add_f32_e32 v4, v220, v4
	v_add_f32_e32 v4, v221, v4
	v_add_f32_e32 v4, v222, v4
	v_add_f32_e32 v4, v223, v4
	v_add_f32_e32 v225, v224, v4
	ds_read2_b64 v[4:7], v226 offset0:128 offset1:130
	ds_read2_b64 v[8:11], v226 offset0:132 offset1:134
	ds_read2_b64 v[12:15], v227 offset0:192 offset1:194
	ds_read2_b64 v[80:83], v228 offset1:2
	ds_read2_b64 v[84:87], v229 offset0:64 offset1:66
	ds_read2_b64 v[88:91], v227 offset0:196 offset1:198
	ds_read2_b64 v[92:95], v228 offset0:4 offset1:6
	ds_read2_b64 v[96:99], v229 offset0:68 offset1:70
	v_exp_f32_e32 v0, v0
	v_cvt_pk_bf16_f32 v100, v183, v184
	v_cvt_pk_bf16_f32 v101, v185, v186
	v_cvt_pk_bf16_f32 v102, v187, v192
	v_pk_mul_f32 v[78:79], v[78:79], v[0:1] op_sel_hi:[1,0]
	v_pk_mul_f32 v[76:77], v[76:77], v[0:1] op_sel_hi:[1,0]
	v_pk_mul_f32 v[74:75], v[74:75], v[0:1] op_sel_hi:[1,0]
	v_pk_mul_f32 v[72:73], v[72:73], v[0:1] op_sel_hi:[1,0]
	v_pk_mul_f32 v[70:71], v[70:71], v[0:1] op_sel_hi:[1,0]
	v_pk_mul_f32 v[68:69], v[68:69], v[0:1] op_sel_hi:[1,0]
	v_pk_mul_f32 v[66:67], v[66:67], v[0:1] op_sel_hi:[1,0]
	v_pk_mul_f32 v[64:65], v[64:65], v[0:1] op_sel_hi:[1,0]
	v_pk_mul_f32 v[62:63], v[62:63], v[0:1] op_sel_hi:[1,0]
	v_pk_mul_f32 v[60:61], v[60:61], v[0:1] op_sel_hi:[1,0]
	v_pk_mul_f32 v[58:59], v[58:59], v[0:1] op_sel_hi:[1,0]
	v_pk_mul_f32 v[56:57], v[56:57], v[0:1] op_sel_hi:[1,0]
	v_pk_mul_f32 v[54:55], v[54:55], v[0:1] op_sel_hi:[1,0]
	v_pk_mul_f32 v[52:53], v[52:53], v[0:1] op_sel_hi:[1,0]
	v_pk_mul_f32 v[50:51], v[50:51], v[0:1] op_sel_hi:[1,0]
	v_pk_mul_f32 v[48:49], v[48:49], v[0:1] op_sel_hi:[1,0]
	v_pk_mul_f32 v[46:47], v[46:47], v[0:1] op_sel_hi:[1,0]
	v_pk_mul_f32 v[44:45], v[44:45], v[0:1] op_sel_hi:[1,0]
	v_pk_mul_f32 v[42:43], v[42:43], v[0:1] op_sel_hi:[1,0]
	v_pk_mul_f32 v[40:41], v[40:41], v[0:1] op_sel_hi:[1,0]
	v_pk_mul_f32 v[38:39], v[38:39], v[0:1] op_sel_hi:[1,0]
	v_pk_mul_f32 v[36:37], v[36:37], v[0:1] op_sel_hi:[1,0]
	v_pk_mul_f32 v[34:35], v[34:35], v[0:1] op_sel_hi:[1,0]
	v_pk_mul_f32 v[32:33], v[32:33], v[0:1] op_sel_hi:[1,0]
	v_pk_mul_f32 v[30:31], v[30:31], v[0:1] op_sel_hi:[1,0]
	v_pk_mul_f32 v[28:29], v[28:29], v[0:1] op_sel_hi:[1,0]
	v_pk_mul_f32 v[26:27], v[26:27], v[0:1] op_sel_hi:[1,0]
	v_pk_mul_f32 v[24:25], v[24:25], v[0:1] op_sel_hi:[1,0]
	v_pk_mul_f32 v[22:23], v[22:23], v[0:1] op_sel_hi:[1,0]
	v_pk_mul_f32 v[20:21], v[20:21], v[0:1] op_sel_hi:[1,0]
	v_pk_mul_f32 v[18:19], v[18:19], v[0:1] op_sel_hi:[1,0]
	v_pk_mul_f32 v[16:17], v[16:17], v[0:1] op_sel_hi:[1,0]
	v_cvt_pk_bf16_f32 v103, v193, v103
	s_waitcnt lgkmcnt(7)
; DI unsigned pk2(float lo, float hi) { const hwf2_t v = {lo, hi}; const hwbf2_t b = __builtin_convertvector(v, hwbf2_t); return __builtin_bit_cast(unsigned, b); }
; DI void lds_barrier() { asm volatile("s_waitcnt lgkmcnt(0)" ::: "memory"); __builtin_amdgcn_s_barrier(); asm volatile("" ::: "memory"); }
; #define ATT_LDV(buf, gi) do { const int _kg = (gi) / NDB, _db = (gi) % NDB; _Pragma("unroll") for (int d = 0; d < 4; ++d) { const bf16_t* vp = Vs + (32 * (4 * _db + d) + l31) * VS + 16 * _kg + 4 * hh; \
;                         const u32x2 lo = *(const u32x2*)vp, hi = *(const u32x2*)(vp + 8); Vf[buf][d].x = lo.x; Vf[buf][d].y = lo.y; Vf[buf][d].z = hi.x; Vf[buf][d].w = hi.y; } } while (0)
; template <int DK, int DV, int KT, bool SAMPLE>
; DI void attn_item(CP c, int l, int qb, int h, unsigned char* sm) {
;     ...
;                 for (int gi = 0; gi < NG; ++gi) { const int kg = gi / NDB, db = gi % NDB, mt = kg >> 1, s2 = kg & 1;
;                     if (gi + 1 < NG) ATT_LDV((gi + 1) & 1, gi + 1);
;                     u32x4 pw; pw.x = pk2(S[mt][8 * s2 + 0], S[mt][8 * s2 + 1]); pw.y = pk2(S[mt][8 * s2 + 2], S[mt][8 * s2 + 3]);
;                     pw.z = pk2(S[mt][8 * s2 + 4], S[mt][8 * s2 + 5]); pw.w = pk2(S[mt][8 * s2 + 6], S[mt][8 * s2 + 7]);
;                     const bf16x8 pf = __builtin_bit_cast(bf16x8, pw);
;                     __builtin_amdgcn_sched_barrier(0);
; #pragma unroll
;                     for (int d = 0; d < 4; ++d) Oacc[4 * db + d] = __builtin_amdgcn_mfma_f32_32x32x16_bf16(__builtin_bit_cast(bf16x8, Vf[gi & 1][d]), pf, Oacc[4 * db + d], 0, 0, 0);
;                     __builtin_amdgcn_sched_barrier(0);
;                 }
;     ...
;             }
;         }
;     }
;     ...
;     const float l_tot = l_run + __shfl_xor(l_run, 32);
;     lds_barrier();
;     if (g == 1 && wave_on) { float* e = Ex + (size_t)wq * (NDT * 16 + 2) * 64;
; #pragma unroll
;         for (int d = 0; d < NDT; ++d)
; #pragma unroll
;             for (int i = 0; i < 16; ++i) e[(d * 16 + i) * 64 + lane] = Oacc[d][i];
;         e[(NDT * 16) * 64 + lane] = m_run; e[(NDT * 16 + 1) * 64 + lane] = l_tot; }
	s_nop 0
	v_mfma_f32_32x32x16_bf16 v[64:79], v[4:7], v[100:103], v[64:79]
	s_waitcnt lgkmcnt(5)
	v_mfma_f32_32x32x16_bf16 v[48:63], v[12:15], v[100:103], v[48:63]
	s_waitcnt lgkmcnt(4)
	v_mfma_f32_32x32x16_bf16 v[32:47], v[80:83], v[100:103], v[32:47]
	s_waitcnt lgkmcnt(3)
	v_mfma_f32_32x32x16_bf16 v[16:31], v[84:87], v[100:103], v[16:31]
	ds_read2_b64 v[4:7], v226 offset0:136 offset1:138
	ds_read2_b64 v[12:15], v227 offset0:200 offset1:202
	ds_read2_b64 v[80:83], v228 offset0:8 offset1:10
	ds_read2_b64 v[84:87], v229 offset0:72 offset1:74
	v_cvt_pk_bf16_f32 v100, v104, v105
	v_cvt_pk_bf16_f32 v101, v106, v107
	v_cvt_pk_bf16_f32 v102, v108, v109
	v_cvt_pk_bf16_f32 v103, v110, v111
	s_nop 1
	v_mfma_f32_32x32x16_bf16 v[64:79], v[8:11], v[100:103], v[64:79]
	s_waitcnt lgkmcnt(6)
	v_mfma_f32_32x32x16_bf16 v[48:63], v[88:91], v[100:103], v[48:63]
	s_waitcnt lgkmcnt(5)
	v_mfma_f32_32x32x16_bf16 v[32:47], v[92:95], v[100:103], v[32:47]
	s_waitcnt lgkmcnt(4)
	v_mfma_f32_32x32x16_bf16 v[16:31], v[96:99], v[100:103], v[16:31]
	ds_read2_b64 v[8:11], v226 offset0:140 offset1:142
	ds_read2_b64 v[88:91], v227 offset0:204 offset1:206
	ds_read2_b64 v[92:95], v228 offset0:12 offset1:14
	ds_read2_b64 v[96:99], v229 offset0:76 offset1:78
	v_cvt_pk_bf16_f32 v100, v204, v205
	v_cvt_pk_bf16_f32 v101, v206, v207
	v_cvt_pk_bf16_f32 v102, v213, v214
	v_cvt_pk_bf16_f32 v103, v215, v216
	s_waitcnt lgkmcnt(7)
	s_nop 0
	v_mfma_f32_32x32x16_bf16 v[64:79], v[4:7], v[100:103], v[64:79]
	s_waitcnt lgkmcnt(6)
	v_mfma_f32_32x32x16_bf16 v[48:63], v[12:15], v[100:103], v[48:63]
	s_waitcnt lgkmcnt(5)
	v_mfma_f32_32x32x16_bf16 v[32:47], v[80:83], v[100:103], v[32:47]
	s_waitcnt lgkmcnt(4)
	v_mfma_f32_32x32x16_bf16 v[16:31], v[84:87], v[100:103], v[16:31]
	v_cvt_pk_bf16_f32 v4, v217, v218
	v_cvt_pk_bf16_f32 v5, v219, v220
	v_cvt_pk_bf16_f32 v6, v221, v222
	v_cvt_pk_bf16_f32 v7, v223, v224
	s_waitcnt lgkmcnt(3)
	s_nop 0
	v_mfma_f32_32x32x16_bf16 v[64:79], v[8:11], v[4:7], v[64:79]
	s_waitcnt lgkmcnt(2)
	v_mfma_f32_32x32x16_bf16 v[48:63], v[88:91], v[4:7], v[48:63]
	s_waitcnt lgkmcnt(1)
	v_mfma_f32_32x32x16_bf16 v[32:47], v[92:95], v[4:7], v[32:47]
	s_waitcnt lgkmcnt(0)
	v_mfma_f32_32x32x16_bf16 v[16:31], v[96:99], v[4:7], v[16:31]
	ds_read_b128 v[80:83], v181
	ds_read_b128 v[214:217], v181 offset:32
	ds_read_b128 v[234:237], v181 offset:64
	ds_read_b128 v[238:241], v181 offset:96
	v_fmac_f32_e32 v225, v177, v0
	v_mov_b32_e32 v177, v225
	v_mov_b32_e32 v183, v3
	s_branch .LBB0_646
.LBB0_651:
	s_or_b64 exec, exec, s[12:13]
	s_setprio 0
	v_and_b32_e32 v2, 64, v196
	v_xor_b32_e32 v0, 32, v196
	v_add_u32_e32 v2, 64, v2
	v_cmp_lt_i32_e32 vcc, v0, v2
	s_waitcnt lgkmcnt(0)
	s_barrier
	s_nop 0
	v_cndmask_b32_e32 v0, v196, v0, vcc
	v_lshlrev_b32_e32 v0, 2, v0
	ds_bpermute_b32 v0, v0, v177
	v_cmp_eq_u32_e32 vcc, 1, v154
	s_waitcnt lgkmcnt(0)
	v_add_f32_e32 v4, v177, v0
	v_lshlrev_b32_e32 v0, 2, v174
	s_and_saveexec_b64 s[12:13], vcc
	s_cbranch_execz .LBB0_653
	v_mul_u32_u24_e32 v2, 0x4200, v173
	v_add3_u32 v2, 0, v2, v0
	v_add_u32_e32 v3, 0xc800, v2
	ds_write2st64_b32 v2, v64, v65 offset0:200 offset1:201
	ds_write2st64_b32 v2, v66, v67 offset0:202 offset1:203
	ds_write2st64_b32 v2, v68, v69 offset0:204 offset1:205
	ds_write2st64_b32 v2, v70, v71 offset0:206 offset1:207
	ds_write2st64_b32 v2, v72, v73 offset0:208 offset1:209
	ds_write2st64_b32 v2, v74, v75 offset0:210 offset1:211
	ds_write2st64_b32 v2, v76, v77 offset0:212 offset1:213
	ds_write2st64_b32 v2, v78, v79 offset0:214 offset1:215
	ds_write2st64_b32 v2, v48, v49 offset0:216 offset1:217
	ds_write2st64_b32 v2, v50, v51 offset0:218 offset1:219
	ds_write2st64_b32 v2, v52, v53 offset0:220 offset1:221
	ds_write2st64_b32 v2, v54, v55 offset0:222 offset1:223
	ds_write2st64_b32 v2, v56, v57 offset0:224 offset1:225
	ds_write2st64_b32 v2, v58, v59 offset0:226 offset1:227
	ds_write2st64_b32 v2, v60, v61 offset0:228 offset1:229
	ds_write2st64_b32 v2, v62, v63 offset0:230 offset1:231
	ds_write2st64_b32 v2, v32, v33 offset0:232 offset1:233
	ds_write2st64_b32 v2, v34, v35 offset0:234 offset1:235
	ds_write2st64_b32 v2, v36, v37 offset0:236 offset1:237
	ds_write2st64_b32 v2, v38, v39 offset0:238 offset1:239
	ds_write2st64_b32 v2, v40, v41 offset0:240 offset1:241
	ds_write2st64_b32 v2, v42, v43 offset0:242 offset1:243
	ds_write2st64_b32 v2, v44, v45 offset0:244 offset1:245
	ds_write2st64_b32 v2, v46, v47 offset0:246 offset1:247
	ds_write2st64_b32 v2, v16, v17 offset0:248 offset1:249
	ds_write2st64_b32 v2, v18, v19 offset0:250 offset1:251
	ds_write2st64_b32 v2, v20, v21 offset0:252 offset1:253
	ds_write2st64_b32 v2, v22, v23 offset0:254 offset1:255
	ds_write2st64_b32 v3, v24, v25 offset0:56 offset1:57
	ds_write2st64_b32 v3, v26, v27 offset0:58 offset1:59
	ds_write2st64_b32 v3, v28, v29 offset0:60 offset1:61
	ds_write2st64_b32 v3, v30, v31 offset0:62 offset1:63
	ds_write2st64_b32 v3, v183, v4 offset0:64 offset1:65
